# adds: rmsnorm row loops (xn chunk 0 / next chunk) load the next row one iteration ahead into a second register set
# speedup vs baseline: 1.0202x; 1.0012x over previous
; DI unsigned pk2(float lo, float hi) { f32x2_t v = {lo, hi}; bf16x2_t b = __builtin_convertvector(v, bf16x2_t); return __builtin_bit_cast(unsigned, b); }
; DI void p0_xn(KP A, bf16* XN, int grow0, int Tc, int wave, int lane, int G) {
;     const int gw = blockIdx.x * NWAVES + wave, NGW = G * NWAVES;
;     const f32x4* gp = (const f32x4*)kin(A, I_N1G) + lane;
;     f32x4 g[4];
; #pragma unroll
;     for (int j = 0; j < 4; ++j) g[j] = gp[64 * j];
;     for (int m = gw; m < Tc; m += NGW) {
;         const int grow = grow0 + m; const float* xr = (grow < 65536) ? kin(A, I_XP) + (size_t)grow * 1024 : kin(A, I_XS) + (size_t)(grow - 65536) * 1024;
;         const f32x4* xv = (const f32x4*)xr + lane; f32x4 v[4]; float s = 0.f;
; #pragma unroll
;         for (int j = 0; j < 4; ++j) { v[j] = xv[64 * j]; s += (v[j].x * v[j].x + v[j].y * v[j].y) + (v[j].z * v[j].z + v[j].w * v[j].w); }
;         const float rs = __builtin_amdgcn_rsqf(wave_sum(s) * (1.0f / 1024.0f) + EPS_);
;         v2u* o8 = (v2u*)(XN + (size_t)m * 1024) + lane;
; #pragma unroll
;         for (int j = 0; j < 4; ++j) { v2u w; w.x = pk2(v[j].x * rs * g[j].x, v[j].y * rs * g[j].y); w.y = pk2(v[j].z * rs * g[j].z, v[j].w * rs * g[j].w); o8[64 * j] = w; }
;     }
.LBB0_82:
	s_or_b64 exec, exec, s[4:5]
	s_lshl_b32 s2, s2, 11
	s_cmp_ge_i32 s14, s2
	v_mbcnt_lo_u32_b32 v1, -1, 0
	s_cbranch_scc1 .LBB0_85
	s_load_dwordx2 s[4:5], s[12:13], 0x10
	v_lshlrev_b32_e32 v19, 4, v18
	v_mbcnt_hi_u32_b32 v26, -1, v1
	v_xor_b32_e32 v22, 2, v26
	v_xor_b32_e32 v23, 4, v26
	s_waitcnt lgkmcnt(0)
	global_load_dwordx4 v[2:5], v19, s[4:5] offset:3072
	global_load_dwordx4 v[6:9], v19, s[4:5] offset:2048
	global_load_dwordx4 v[10:13], v19, s[4:5] offset:1024
	global_load_dwordx4 v[14:17], v19, s[4:5]
	v_and_b32_e32 v19, 64, v26
	v_add_u32_e32 v27, 64, v19
	v_xor_b32_e32 v19, 1, v26
	v_cmp_lt_i32_e32 vcc, v19, v27
	v_xor_b32_e32 v24, 8, v26
	s_ashr_i32 s15, s14, 31
	v_cndmask_b32_e32 v19, v26, v19, vcc
	v_cmp_lt_i32_e32 vcc, v22, v27
	s_lshl_b32 s1, s1, 11
	v_xor_b32_e32 v25, 16, v26
	v_cndmask_b32_e32 v22, v26, v22, vcc
	v_cmp_lt_i32_e32 vcc, v23, v27
	s_lshl_b64 s[4:5], s[14:15], 11
	v_xor_b32_e32 v28, 32, v26
	v_cndmask_b32_e32 v23, v26, v23, vcc
	v_cmp_lt_i32_e32 vcc, v24, v27
	s_add_u32 s4, s16, s4
	v_mov_b32_e32 v21, 0
	v_cndmask_b32_e32 v24, v26, v24, vcc
	v_cmp_lt_i32_e32 vcc, v25, v27
	s_addc_u32 s5, s17, s5
	s_add_i32 s0, s0, s1
	v_cndmask_b32_e32 v25, v26, v25, vcc
	v_cmp_lt_i32_e32 vcc, v28, v27
	v_readlane_b32 s1, v255, 2
	v_lshl_add_u64 v[20:21], s[4:5], 0, v[20:21]
	v_cndmask_b32_e32 v26, v26, v28, vcc
	s_mov_b64 s[4:5], 0x2d00600
	s_ashr_i32 s67, s66, 31
	s_add_i32 s0, s0, s1
	v_lshlrev_b32_e32 v19, 2, v19
	v_lshlrev_b32_e32 v22, 2, v22
	v_lshlrev_b32_e32 v23, 2, v23
	v_lshlrev_b32_e32 v24, 2, v24
	v_lshlrev_b32_e32 v25, 2, v25
	v_lshlrev_b32_e32 v26, 2, v26
	v_lshl_add_u64 v[20:21], v[20:21], 0, s[4:5]
	s_lshl_b64 s[4:5], s[66:67], 11
	s_ashr_i32 s1, s0, 31
	v_lshlrev_b32_e32 v18, 4, v18
	v_mov_b32_e32 v27, 0x358637bd
	s_add_i32 s3, s0, 0xffff0000
	s_cmp_lt_i32 s0, 0x10000
	s_cselect_b32 s8, s0, s3
	s_cselect_b32 s3, 0, 8
	s_cselect_b32 s9, s1, 0
	s_add_u32 s10, s12, s3
	s_addc_u32 s11, s13, 0
	s_load_dwordx2 s[10:11], s[10:11], 0x0
	s_lshl_b64 s[8:9], s[8:9], 12
	s_waitcnt lgkmcnt(0)
	s_add_u32 s8, s10, s8
	s_addc_u32 s9, s11, s9
	global_load_dwordx4 v[28:31], v18, s[8:9]
	global_load_dwordx4 v[32:35], v18, s[8:9] offset:1024
	global_load_dwordx4 v[36:39], v18, s[8:9] offset:2048
	global_load_dwordx4 v[40:43], v18, s[8:9] offset:3072
	s_waitcnt vmcnt(0)
.LBB0_84:
	s_add_i32 s14, s14, s66
	s_add_u32 s0, s0, s66
	s_addc_u32 s1, s1, s67
	s_cmp_lt_i32 s14, s2
	s_cselect_b32 s32, 1, 0
	s_cbranch_scc0 .Lxn_a_nopf
	s_add_i32 s3, s0, 0xffff0000
	s_cmp_lt_i32 s0, 0x10000
	s_cselect_b32 s8, s0, s3
	s_cselect_b32 s3, 0, 8
	s_cselect_b32 s9, s1, 0
	s_add_u32 s10, s12, s3
	s_addc_u32 s11, s13, 0
	s_load_dwordx2 s[10:11], s[10:11], 0x0
	s_lshl_b64 s[8:9], s[8:9], 12
	s_waitcnt lgkmcnt(0)
	s_add_u32 s8, s10, s8
	s_addc_u32 s9, s11, s9
	global_load_dwordx4 v[100:103], v18, s[8:9]
	global_load_dwordx4 v[104:107], v18, s[8:9] offset:1024
	global_load_dwordx4 v[108:111], v18, s[8:9] offset:2048
	global_load_dwordx4 v[112:115], v18, s[8:9] offset:3072
; DI unsigned pk2(float lo, float hi) { f32x2_t v = {lo, hi}; bf16x2_t b = __builtin_convertvector(v, bf16x2_t); return __builtin_bit_cast(unsigned, b); }
; DI void p0_xn(KP A, bf16* XN, int grow0, int Tc, int wave, int lane, int G) {
;     ...
;         const f32x4* xv = (const f32x4*)xr + lane; f32x4 v[4]; float s = 0.f;
; #pragma unroll
;         for (int j = 0; j < 4; ++j) { v[j] = xv[64 * j]; s += (v[j].x * v[j].x + v[j].y * v[j].y) + (v[j].z * v[j].z + v[j].w * v[j].w); }
;         const float rs = __builtin_amdgcn_rsqf(wave_sum(s) * (1.0f / 1024.0f) + EPS_);
;         v2u* o8 = (v2u*)(XN + (size_t)m * 1024) + lane;
; #pragma unroll
;         for (int j = 0; j < 4; ++j) { v2u w; w.x = pk2(v[j].x * rs * g[j].x, v[j].y * rs * g[j].y); w.y = pk2(v[j].z * rs * g[j].z, v[j].w * rs * g[j].w); o8[64 * j] = w; }
;     }
.Lxn_a_nopf:
	s_nop 0
	v_pk_mul_f32 v[44:45], v[30:31], v[30:31]
	v_pk_mul_f32 v[46:47], v[28:29], v[28:29]
	s_nop 0
	v_pk_mul_f32 v[48:49], v[34:35], v[34:35]
	v_pk_mul_f32 v[50:51], v[32:33], v[32:33]
	v_pk_mov_b32 v[56:57], v[46:47], v[44:45] op_sel:[1,0]
	v_mov_b32_e32 v47, v45
	v_pk_mov_b32 v[44:45], v[50:51], v[48:49] op_sel:[1,0]
	v_mov_b32_e32 v51, v49
	s_nop 0
	v_mul_f32_e32 v55, v40, v40
	v_mul_f32_e32 v52, v37, v37
	v_mul_f32_e32 v54, v39, v39
	v_pk_add_f32 v[46:47], v[56:57], v[46:47]
	v_pk_add_f32 v[44:45], v[44:45], v[50:51]
	v_mul_f32_e32 v58, v41, v41
	v_mul_f32_e32 v59, v42, v42
	v_mul_f32_e32 v60, v43, v43
	v_pk_fma_f32 v[48:49], v[36:37], v[36:37], v[52:53] op_sel_hi:[1,1,0]
	v_pk_fma_f32 v[52:53], v[38:39], v[38:39], v[54:55] op_sel_hi:[1,1,0]
	v_pk_add_f32 v[46:47], v[46:47], v[46:47] op_sel:[0,1] op_sel_hi:[1,0]
	v_pk_add_f32 v[44:45], v[44:45], v[44:45] op_sel:[0,1] op_sel_hi:[1,0]
	v_mov_b32_e32 v49, v59
	v_mov_b32_e32 v53, v60
	v_mov_b32_e32 v47, v55
	v_mov_b32_e32 v45, v58
	v_pk_add_f32 v[48:49], v[48:49], v[52:53]
	v_pk_add_f32 v[44:45], v[46:47], v[44:45]
	s_nop 0
	v_pk_add_f32 v[44:45], v[44:45], v[48:49]
	s_nop 0
	v_add_f32_e32 v44, v44, v45
	ds_bpermute_b32 v45, v19, v44
	s_waitcnt lgkmcnt(0)
	v_add_f32_e32 v44, v44, v45
	ds_bpermute_b32 v45, v22, v44
	s_waitcnt lgkmcnt(0)
	v_add_f32_e32 v44, v44, v45
	ds_bpermute_b32 v45, v23, v44
	s_waitcnt lgkmcnt(0)
	v_add_f32_e32 v44, v44, v45
	ds_bpermute_b32 v45, v24, v44
	s_waitcnt lgkmcnt(0)
	v_add_f32_e32 v44, v44, v45
	ds_bpermute_b32 v45, v25, v44
	s_waitcnt lgkmcnt(0)
	v_add_f32_e32 v44, v44, v45
	ds_bpermute_b32 v45, v26, v44
	s_waitcnt lgkmcnt(0)
	v_add_f32_e32 v44, v44, v45
	v_fmamk_f32 v44, v44, 0x3a800000, v27
	v_rsq_f32_e32 v44, v44
	s_nop 0
	v_pk_mul_f32 v[28:29], v[28:29], v[44:45] op_sel_hi:[1,0]
	v_pk_mul_f32 v[30:31], v[30:31], v[44:45] op_sel_hi:[1,0]
	v_pk_mul_f32 v[32:33], v[32:33], v[44:45] op_sel_hi:[1,0]
	v_pk_mul_f32 v[34:35], v[34:35], v[44:45] op_sel_hi:[1,0]
	v_pk_mul_f32 v[36:37], v[36:37], v[44:45] op_sel_hi:[1,0]
	v_pk_mul_f32 v[38:39], v[38:39], v[44:45] op_sel_hi:[1,0]
	v_pk_mul_f32 v[40:41], v[40:41], v[44:45] op_sel_hi:[1,0]
	v_pk_mul_f32 v[42:43], v[42:43], v[44:45] op_sel_hi:[1,0]
	v_pk_mul_f32 v[28:29], v[14:15], v[28:29]
	v_pk_mul_f32 v[30:31], v[16:17], v[30:31]
	v_pk_mul_f32 v[32:33], v[10:11], v[32:33]
	v_pk_mul_f32 v[34:35], v[12:13], v[34:35]
	v_pk_mul_f32 v[36:37], v[6:7], v[36:37]
	v_pk_mul_f32 v[38:39], v[8:9], v[38:39]
	v_pk_mul_f32 v[40:41], v[2:3], v[40:41]
	v_pk_mul_f32 v[42:43], v[4:5], v[42:43]
	v_cvt_pk_bf16_f32 v28, v28, v29
	v_cvt_pk_bf16_f32 v29, v30, v31
	v_cvt_pk_bf16_f32 v30, v32, v33
	v_cvt_pk_bf16_f32 v31, v34, v35
	v_cvt_pk_bf16_f32 v32, v36, v37
	v_cvt_pk_bf16_f32 v33, v38, v39
	v_cvt_pk_bf16_f32 v34, v40, v41
	v_cvt_pk_bf16_f32 v35, v42, v43
	global_store_dwordx2 v[20:21], v[28:29], off offset:-1536
	global_store_dwordx2 v[20:21], v[30:31], off offset:-1024
	global_store_dwordx2 v[20:21], v[32:33], off offset:-512
	global_store_dwordx2 v[20:21], v[34:35], off
	s_cmp_lg_u32 s32, 0
	s_cbranch_scc0 .Lxn_a_done
	s_waitcnt vmcnt(4)
	v_mov_b32_e32 v28, v100
	v_mov_b32_e32 v29, v101
	v_mov_b32_e32 v30, v102
	v_mov_b32_e32 v31, v103
	v_mov_b32_e32 v32, v104
	v_mov_b32_e32 v33, v105
	v_mov_b32_e32 v34, v106
	v_mov_b32_e32 v35, v107
	v_mov_b32_e32 v36, v108
	v_mov_b32_e32 v37, v109
	v_mov_b32_e32 v38, v110
	v_mov_b32_e32 v39, v111
	v_mov_b32_e32 v40, v112
	v_mov_b32_e32 v41, v113
	v_mov_b32_e32 v42, v114
	v_mov_b32_e32 v43, v115
	v_lshl_add_u64 v[20:21], v[20:21], 0, s[4:5]
	s_branch .LBB0_84
.Lxn_a_done:
.LBB0_85:
	s_load_dwordx2 s[4:5], s[6:7], 0x4
	v_lshrrev_b32_e32 v2, 20, v0
	v_lshrrev_b32_e32 v0, 10, v0
	v_or_b32_e32 v0, v0, v2
	s_movk_i32 s0, 0x3ff
	v_and_or_b32 v0, v0, s0, v179
	v_cmp_eq_u32_e32 vcc, 0, v0
	s_waitcnt lgkmcnt(0)
	s_barrier
	s_and_saveexec_b64 s[8:9], vcc
	s_cbranch_execz .LBB0_95
	buffer_wbl2 sc1
	s_waitcnt vmcnt(0)
	s_load_dwordx2 s[6:7], s[6:7], 0x58
	v_mov_b32_e32 v3, 0
	s_mov_b64 s[10:11], exec
	v_mbcnt_lo_u32_b32 v2, s10, 0
	v_mbcnt_hi_u32_b32 v2, s11, v2
	s_waitcnt lgkmcnt(0)
	global_load_dword v0, v3, s[6:7] offset:40
	v_cmp_eq_u32_e32 vcc, 0, v2
	s_and_saveexec_b64 s[12:13], vcc
	s_cbranch_execz .LBB0_88
	s_bcnt1_i32_b64 s0, s[10:11]
	v_mov_b32_e32 v4, s0
	global_atomic_add v4, v3, v4, s[6:7] offset:32 sc0

; DI unsigned pk2(float lo, float hi) { f32x2_t v = {lo, hi}; bf16x2_t b = __builtin_convertvector(v, bf16x2_t); return __builtin_bit_cast(unsigned, b); }
; DI void p0_xn(KP A, bf16* XN, int grow0, int Tc, int wave, int lane, int G) {
;     const int gw = blockIdx.x * NWAVES + wave, NGW = G * NWAVES;
;     const f32x4* gp = (const f32x4*)kin(A, I_N1G) + lane;
;     f32x4 g[4];
; #pragma unroll
;     for (int j = 0; j < 4; ++j) g[j] = gp[64 * j];
;     for (int m = gw; m < Tc; m += NGW) {
;         const int grow = grow0 + m; const float* xr = (grow < 65536) ? kin(A, I_XP) + (size_t)grow * 1024 : kin(A, I_XS) + (size_t)(grow - 65536) * 1024;
;         const f32x4* xv = (const f32x4*)xr + lane; f32x4 v[4]; float s = 0.f;
; #pragma unroll
;         for (int j = 0; j < 4; ++j) { v[j] = xv[64 * j]; s += (v[j].x * v[j].x + v[j].y * v[j].y) + (v[j].z * v[j].z + v[j].w * v[j].w); }
;         const float rs = __builtin_amdgcn_rsqf(wave_sum(s) * (1.0f / 1024.0f) + EPS_);
;         v2u* o8 = (v2u*)(XN + (size_t)m * 1024) + lane;
; #pragma unroll
;         for (int j = 0; j < 4; ++j) { v2u w; w.x = pk2(v[j].x * rs * g[j].x, v[j].y * rs * g[j].y); w.y = pk2(v[j].z * rs * g[j].z, v[j].w * rs * g[j].w); o8[64 * j] = w; }
;     }
.LBB0_1042:
	s_add_i32 s0, s29, 1
	v_readlane_b32 s1, v255, 4
	s_cmp_ge_i32 s0, s1
	s_cbranch_scc1 .LBB0_99
	v_mov_b32_e32 v1, v179
	s_mov_b64 s[4:5], s[90:91]
	v_readfirstlane_b32 s1, v1
	s_ashr_i32 s2, s1, 6
	s_mov_b32 s1, s29
	s_lshl_b32 s1, s29, 2
	s_ashr_i32 s3, s1, 31
	s_add_u32 s8, s4, s1
	s_addc_u32 s9, s5, s3
	s_load_dword s1, s[8:9], 0xdc
	v_readlane_b32 s3, v255, 2
	s_add_i32 s6, s2, s3
	s_waitcnt lgkmcnt(0)
	s_lshl_b32 s1, s1, 11
	s_cmp_ge_i32 s6, s1
	s_cbranch_scc1 .LBB0_1046
	s_load_dwordx2 s[2:3], s[4:5], 0x10
	v_and_b32_e32 v26, 63, v1
	v_lshlrev_b32_e32 v1, 4, v26
	s_load_dwordx2 s[10:11], s[4:5], 0xb0
	s_load_dword s7, s[8:9], 0xc4
	v_xor_b32_e32 v19, 2, v194
	s_waitcnt lgkmcnt(0)
	global_load_dwordx4 v[2:5], v1, s[2:3] offset:3072
	global_load_dwordx4 v[6:9], v1, s[2:3] offset:2048
	global_load_dwordx4 v[10:13], v1, s[2:3] offset:1024
	global_load_dwordx4 v[14:17], v1, s[2:3]
	v_and_b32_e32 v1, 64, v194
	v_add_u32_e32 v18, 64, v1
	v_xor_b32_e32 v1, 1, v194
	v_cmp_lt_i32_e32 vcc, v1, v18
	s_load_dword s2, s[4:5], 0xb8
	v_lshlrev_b32_e32 v25, 4, v26
	v_cndmask_b32_e32 v1, v194, v1, vcc
	v_cmp_lt_i32_e32 vcc, v19, v18
	v_lshlrev_b32_e32 v1, 2, v1
	s_waitcnt lgkmcnt(0)
	s_lshl_b32 s2, s2, 11
	v_cndmask_b32_e32 v19, v194, v19, vcc
	v_lshlrev_b32_e32 v20, 2, v19
	v_xor_b32_e32 v19, 4, v194
	v_cmp_lt_i32_e32 vcc, v19, v18
	s_ashr_i32 s3, s2, 31
	s_lshl_b64 s[8:9], s[2:3], 11
	v_cndmask_b32_e32 v19, v194, v19, vcc
	v_lshlrev_b32_e32 v21, 2, v19
	v_xor_b32_e32 v19, 8, v194
	v_cmp_lt_i32_e32 vcc, v19, v18
	s_lshl_b32 s2, s7, 11
	s_ashr_i32 s7, s6, 31
	v_cndmask_b32_e32 v19, v194, v19, vcc
	v_lshlrev_b32_e32 v22, 2, v19
	v_xor_b32_e32 v19, 16, v194
	v_cmp_lt_i32_e32 vcc, v19, v18
	s_lshl_b64 s[12:13], s[6:7], 11
	s_add_u32 s3, s8, s12
	v_cndmask_b32_e32 v19, v194, v19, vcc
	v_lshlrev_b32_e32 v23, 2, v19
	v_xor_b32_e32 v19, 32, v194
	v_cmp_lt_i32_e32 vcc, v19, v18
	s_addc_u32 s7, s9, s13
	s_add_u32 s8, s10, s3
	v_cndmask_b32_e32 v18, v194, v19, vcc
	v_lshlrev_b32_e32 v24, 2, v18
	v_lshlrev_b32_e32 v18, 3, v26
	v_mov_b32_e32 v19, v0
	s_addc_u32 s9, s11, s7
	v_lshl_add_u64 v[18:19], s[8:9], 0, v[18:19]
	s_mov_b64 s[8:9], 0x2d00400
	s_add_i32 s3, s6, s2
	v_lshl_add_u64 v[18:19], v[18:19], 0, s[8:9]
	s_ashr_i32 s7, s3, 31
	s_add_i32 s8, s2, s6
	s_add_i32 s10, s8, 0xffff0000
	s_cmp_lt_i32 s8, 0x10000
	s_cselect_b32 s8, s3, s10
	s_cselect_b32 s10, 0, 8
	s_cselect_b32 s9, s7, 0
	s_add_u32 s10, s4, s10
	s_addc_u32 s11, s5, 0
	s_load_dwordx2 s[10:11], s[10:11], 0x0
	s_lshl_b64 s[8:9], s[8:9], 12
	s_waitcnt lgkmcnt(0)
	s_add_u32 s8, s10, s8
	s_addc_u32 s9, s11, s9
	global_load_dwordx4 v[26:29], v25, s[8:9]
	global_load_dwordx4 v[30:33], v25, s[8:9] offset:1024
	global_load_dwordx4 v[34:37], v25, s[8:9] offset:2048
	global_load_dwordx4 v[38:41], v25, s[8:9] offset:3072
	s_waitcnt vmcnt(0)
.LBB0_1045:
	s_add_i32 s6, s6, s66
	s_add_u32 s3, s3, s66
	s_addc_u32 s7, s7, s67
	s_cmp_lt_i32 s6, s1
	s_cselect_b32 s32, 1, 0
	s_cbranch_scc0 .Lxn_b_nopf
	s_add_i32 s8, s2, s6
	s_add_i32 s10, s8, 0xffff0000
	s_cmp_lt_i32 s8, 0x10000
	s_cselect_b32 s8, s3, s10
	s_cselect_b32 s10, 0, 8
	s_cselect_b32 s9, s7, 0
	s_add_u32 s10, s4, s10
	s_addc_u32 s11, s5, 0
	s_load_dwordx2 s[10:11], s[10:11], 0x0
	s_lshl_b64 s[8:9], s[8:9], 12
	s_waitcnt lgkmcnt(0)
	s_add_u32 s8, s10, s8
	s_addc_u32 s9, s11, s9
	global_load_dwordx4 v[100:103], v25, s[8:9]
	global_load_dwordx4 v[104:107], v25, s[8:9] offset:1024
	global_load_dwordx4 v[108:111], v25, s[8:9] offset:2048
	global_load_dwordx4 v[112:115], v25, s[8:9] offset:3072
; DI unsigned pk2(float lo, float hi) { f32x2_t v = {lo, hi}; bf16x2_t b = __builtin_convertvector(v, bf16x2_t); return __builtin_bit_cast(unsigned, b); }
; DI void p0_xn(KP A, bf16* XN, int grow0, int Tc, int wave, int lane, int G) {
;     ...
;         const f32x4* xv = (const f32x4*)xr + lane; f32x4 v[4]; float s = 0.f;
; #pragma unroll
;         for (int j = 0; j < 4; ++j) { v[j] = xv[64 * j]; s += (v[j].x * v[j].x + v[j].y * v[j].y) + (v[j].z * v[j].z + v[j].w * v[j].w); }
;         const float rs = __builtin_amdgcn_rsqf(wave_sum(s) * (1.0f / 1024.0f) + EPS_);
;         v2u* o8 = (v2u*)(XN + (size_t)m * 1024) + lane;
; #pragma unroll
;         for (int j = 0; j < 4; ++j) { v2u w; w.x = pk2(v[j].x * rs * g[j].x, v[j].y * rs * g[j].y); w.y = pk2(v[j].z * rs * g[j].z, v[j].w * rs * g[j].w); o8[64 * j] = w; }
; __device__ __forceinline__ void xcd_barrier(const XcdBarrier& b) {
;     asm volatile("s_waitcnt vmcnt(0)" ::: "memory");
;     __syncthreads();
;     if (threadIdx.x == 0) {
;         unsigned* bar = b.bar;
;         __builtin_amdgcn_s_waitcnt(0);
;         unsigned nloc = b.st[0], nx = b.st[1];
;         if (nloc == 0u) { xcd_barrier_complete(bar, b.x, nloc, nx); b.st[0] = nloc; b.st[1] = nx; }
.Lxn_b_nopf:
	s_nop 0
	v_pk_mul_f32 v[42:43], v[28:29], v[28:29]
	v_pk_mul_f32 v[44:45], v[26:27], v[26:27]
	s_nop 0
	v_pk_mul_f32 v[46:47], v[32:33], v[32:33]
	v_pk_mul_f32 v[48:49], v[30:31], v[30:31]
	v_pk_mov_b32 v[54:55], v[44:45], v[42:43] op_sel:[1,0]
	v_mov_b32_e32 v45, v43
	v_pk_mov_b32 v[42:43], v[48:49], v[46:47] op_sel:[1,0]
	v_mov_b32_e32 v49, v47
	s_nop 0
	v_mul_f32_e32 v53, v38, v38
	v_mul_f32_e32 v50, v35, v35
	v_mul_f32_e32 v52, v37, v37
	v_pk_add_f32 v[44:45], v[54:55], v[44:45]
	v_pk_add_f32 v[42:43], v[42:43], v[48:49]
	v_mul_f32_e32 v56, v39, v39
	v_mul_f32_e32 v57, v40, v40
	v_mul_f32_e32 v58, v41, v41
	v_pk_fma_f32 v[46:47], v[34:35], v[34:35], v[50:51] op_sel_hi:[1,1,0]
	v_pk_fma_f32 v[50:51], v[36:37], v[36:37], v[52:53] op_sel_hi:[1,1,0]
	v_pk_add_f32 v[44:45], v[44:45], v[44:45] op_sel:[0,1] op_sel_hi:[1,0]
	v_pk_add_f32 v[42:43], v[42:43], v[42:43] op_sel:[0,1] op_sel_hi:[1,0]
	v_mov_b32_e32 v47, v57
	v_mov_b32_e32 v51, v58
	v_mov_b32_e32 v45, v53
	v_mov_b32_e32 v43, v56
	v_pk_add_f32 v[46:47], v[46:47], v[50:51]
	v_pk_add_f32 v[42:43], v[44:45], v[42:43]
	s_nop 0
	v_pk_add_f32 v[42:43], v[42:43], v[46:47]
	s_nop 0
	v_add_f32_e32 v42, v42, v43
	ds_bpermute_b32 v43, v1, v42
	s_waitcnt lgkmcnt(0)
	v_add_f32_e32 v42, v42, v43
	ds_bpermute_b32 v43, v20, v42
	s_waitcnt lgkmcnt(0)
	v_add_f32_e32 v42, v42, v43
	ds_bpermute_b32 v43, v21, v42
	s_waitcnt lgkmcnt(0)
	v_add_f32_e32 v42, v42, v43
	ds_bpermute_b32 v43, v22, v42
	s_waitcnt lgkmcnt(0)
	v_add_f32_e32 v42, v42, v43
	ds_bpermute_b32 v43, v23, v42
	s_waitcnt lgkmcnt(0)
	v_add_f32_e32 v42, v42, v43
	ds_bpermute_b32 v43, v24, v42
	s_waitcnt lgkmcnt(0)
	v_add_f32_e32 v42, v42, v43
	v_fmamk_f32 v42, v42, 0x3a800000, v188
	v_rsq_f32_e32 v42, v42
	s_nop 0
	v_pk_mul_f32 v[26:27], v[26:27], v[42:43] op_sel_hi:[1,0]
	v_pk_mul_f32 v[28:29], v[28:29], v[42:43] op_sel_hi:[1,0]
	v_pk_mul_f32 v[30:31], v[30:31], v[42:43] op_sel_hi:[1,0]
	v_pk_mul_f32 v[32:33], v[32:33], v[42:43] op_sel_hi:[1,0]
	v_pk_mul_f32 v[34:35], v[34:35], v[42:43] op_sel_hi:[1,0]
	v_pk_mul_f32 v[36:37], v[36:37], v[42:43] op_sel_hi:[1,0]
	v_pk_mul_f32 v[38:39], v[38:39], v[42:43] op_sel_hi:[1,0]
	v_pk_mul_f32 v[40:41], v[40:41], v[42:43] op_sel_hi:[1,0]
	v_pk_mul_f32 v[26:27], v[14:15], v[26:27]
	v_pk_mul_f32 v[28:29], v[16:17], v[28:29]
	v_pk_mul_f32 v[30:31], v[10:11], v[30:31]
	v_pk_mul_f32 v[32:33], v[12:13], v[32:33]
	v_pk_mul_f32 v[34:35], v[6:7], v[34:35]
	v_pk_mul_f32 v[36:37], v[8:9], v[36:37]
	v_pk_mul_f32 v[38:39], v[2:3], v[38:39]
	v_pk_mul_f32 v[40:41], v[4:5], v[40:41]
	v_cvt_pk_bf16_f32 v26, v26, v27
	v_cvt_pk_bf16_f32 v27, v28, v29
	v_cvt_pk_bf16_f32 v28, v30, v31
	v_cvt_pk_bf16_f32 v29, v32, v33
	v_cvt_pk_bf16_f32 v30, v34, v35
	v_cvt_pk_bf16_f32 v31, v36, v37
	v_cvt_pk_bf16_f32 v32, v38, v39
	v_cvt_pk_bf16_f32 v33, v40, v41
	global_store_dwordx2 v[18:19], v[26:27], off offset:-1024
	global_store_dwordx2 v[18:19], v[28:29], off offset:-512
	global_store_dwordx2 v[18:19], v[30:31], off
	global_store_dwordx2 v[18:19], v[32:33], off offset:512
	s_cmp_lg_u32 s32, 0
	s_cbranch_scc0 .Lxn_b_done
	s_waitcnt vmcnt(4)
	v_mov_b32_e32 v26, v100
	v_mov_b32_e32 v27, v101
	v_mov_b32_e32 v28, v102
	v_mov_b32_e32 v29, v103
	v_mov_b32_e32 v30, v104
	v_mov_b32_e32 v31, v105
	v_mov_b32_e32 v32, v106
	v_mov_b32_e32 v33, v107
	v_mov_b32_e32 v34, v108
	v_mov_b32_e32 v35, v109
	v_mov_b32_e32 v36, v110
	v_mov_b32_e32 v37, v111
	v_mov_b32_e32 v38, v112
	v_mov_b32_e32 v39, v113
	v_mov_b32_e32 v40, v114
	v_mov_b32_e32 v41, v115
	v_lshl_add_u64 v[18:19], v[18:19], 0, s[70:71]
	s_branch .LBB0_1045
.Lxn_b_done:
.LBB0_1046:
	s_mov_b64 s[6:7], s[90:91]
	s_getreg_b32 s1, hwreg(HW_REG_XCC_ID, 0, 4)
	s_waitcnt vmcnt(0)
	s_barrier
	s_mov_b64 s[4:5], exec
	v_readlane_b32 s2, v255, 0
	v_readlane_b32 s3, v255, 1
	s_and_b64 s[2:3], s[4:5], s[2:3]
	s_mov_b64 exec, s[2:3]
	s_cbranch_execz .LBB0_98
	v_readlane_b32 s2, v255, 8
	s_load_dwordx2 s[6:7], s[6:7], 0xb0
	s_waitcnt vmcnt(0) expcnt(0) lgkmcnt(0)
	v_mov_b32_e32 v1, s2
	ds_read_b32 v3, v1
	v_readlane_b32 s2, v255, 9
	s_and_b32 s1, s1, 15
	s_waitcnt lgkmcnt(0)
	v_cmp_ne_u32_e32 vcc, 0, v3
	v_mov_b32_e32 v1, s2
	ds_read_b32 v1, v1
	s_cbranch_vccnz .LBB0_1062
	s_add_u32 s8, s6, 0x80200
	s_addc_u32 s9, s7, 0
	s_add_u32 s10, s6, 0x80400
	s_addc_u32 s11, s7, 0
	s_add_u32 s12, s6, 0x80500
	s_addc_u32 s13, s7, 0
	s_add_u32 s14, s6, 0x80600
	s_addc_u32 s15, s7, 0
	s_add_u32 s16, s6, 0x80700
	s_addc_u32 s17, s7, 0
	s_add_u32 s18, s6, 0x80800
	s_addc_u32 s19, s7, 0
	s_add_u32 s20, s6, 0x80900
	s_addc_u32 s21, s7, 0
	s_add_u32 s24, s6, 0x80a00
	s_addc_u32 s25, s7, 0
	s_add_u32 s26, s6, 0x80b00
	s_addc_u32 s27, s7, 0
	s_add_u32 s58, s6, 0x80c00
	s_addc_u32 s59, s7, 0
	s_add_u32 s60, s6, 0x80d00
	s_addc_u32 s61, s7, 0
	s_add_u32 s62, s6, 0x80e00
	s_addc_u32 s63, s7, 0
	s_add_u32 s64, s6, 0x80f00
	s_addc_u32 s65, s7, 0
	s_add_u32 s66, s6, 0x81000
	s_addc_u32 s67, s7, 0
	s_add_u32 s68, s6, 0x81100
	s_addc_u32 s69, s7, 0
	s_add_u32 s70, s6, 0x81200
	s_addc_u32 s71, s7, 0
	s_add_u32 s72, s6, 0x81300
	s_addc_u32 s73, s7, 0
	s_mov_b32 s2, 1
	s_branch .LBB0_1050
